# v64 + O3 q-up epilogue rows staged through wave-private LDS and stored as 16-byte row chunks
# baseline (speedup 1.0000x reference)
.LBB0_491:
	s_or_b64 exec, exec, s[2:3]
	v_add_u32_e32 v5, s9, v98
	v_ashrrev_i32_e32 v5, 7, v5
	s_movk_i32 s0, 0x60
	v_mul_lo_u32 v36, v5, s0
	v_mov_b64_e32 v[38:39], s[66:67]
	v_mov_b32_e32 v1, v0
	v_ashrrev_i32_e32 v37, 31, v36
	v_mad_i64_i32 v[38:39], s[0:1], v80, s17, v[38:39]
	v_lshl_add_u64 v[36:37], v[36:37], 1, v[38:39]
	v_pk_mul_f32 v[38:39], v[76:77], v[0:1]
	v_pk_mul_f32 v[40:41], v[78:79], v[0:1]
	v_lshlrev_b32_e32 v128, 1, v99
	v_pk_mul_f32 v[38:39], v[96:97], v[38:39]
	v_pk_mul_f32 v[40:41], v[94:95], v[40:41]
	v_lshl_add_u64 v[36:37], v[36:37], 0, v[128:129]
	v_cvt_pk_bf16_f32 v38, v38, v39
	v_cvt_pk_bf16_f32 v39, v40, v41
	v_and_b32_e32 v230, 31, v155
	v_bfe_u32 v231, v155, 5, 1
	v_lshrrev_b32_e32 v232, 6, v155
	v_mul_u32_u24_e32 v232, 0x1a00, v232
	v_mul_u32_u24_e32 v233, 0xd0, v230
	v_add_u32_e32 v233, v233, v232
	v_lshl_add_u32 v233, v231, 3, v233
	v_lshlrev_b32_e32 v238, 3, v231
	v_bfe_u32 v234, v155, 3, 3
	v_and_b32_e32 v235, 7, v155
	v_mul_u32_u24_e32 v236, 0xd0, v234
	v_add_u32_e32 v236, v236, v232
	v_lshl_add_u32 v236, v235, 4, v236
	v_sub_u32_e32 v237, v234, v230
	v_mul_i32_i24_e32 v237, 0x600, v237
	v_lshl_add_u32 v237, v235, 4, v237
	v_sub_u32_e32 v246, v237, v238
	v_ashrrev_i32_e32 v247, 31, v246
	v_lshl_add_u64 v[244:245], v[36:37], 0, v[246:247]
	v_bfe_u32 v234, v155, 2, 4
	v_and_b32_e32 v235, 3, v155
	v_mul_u32_u24_e32 v239, 0xd0, v234
	v_add_u32_e32 v239, v239, v232
	v_lshl_add_u32 v239, v235, 4, v239
	v_add_u32_e32 v239, 0x80, v239
	v_sub_u32_e32 v237, v234, v230
	v_mul_i32_i24_e32 v237, 0x600, v237
	v_lshl_add_u32 v237, v235, 4, v237
	v_add_u32_e32 v237, 0x80, v237
	v_sub_u32_e32 v246, v237, v238
	v_ashrrev_i32_e32 v247, 31, v246
	v_lshl_add_u64 v[198:199], v[36:37], 0, v[246:247]
	v_mov_b32_e32 v196, 0x3000
	v_mov_b32_e32 v197, 0
	v_mov_b32_e32 v194, 0x6000
	v_mov_b32_e32 v195, 0
	ds_write_b64 v233, v[38:39]
	v_pk_mul_f32 v[38:39], v[72:73], v[0:1]
	v_pk_mul_f32 v[40:41], v[74:75], v[0:1]
	v_pk_mul_f32 v[38:39], v[92:93], v[38:39]
	v_pk_mul_f32 v[40:41], v[90:91], v[40:41]
	v_cvt_pk_bf16_f32 v38, v38, v39
	v_cvt_pk_bf16_f32 v39, v40, v41
	ds_write_b64 v233, v[38:39] offset:16
	v_pk_mul_f32 v[38:39], v[68:69], v[0:1]
	v_pk_mul_f32 v[40:41], v[70:71], v[0:1]
	v_pk_mul_f32 v[38:39], v[88:89], v[38:39]
	v_pk_mul_f32 v[40:41], v[86:87], v[40:41]
	v_cvt_pk_bf16_f32 v38, v38, v39
	v_cvt_pk_bf16_f32 v39, v40, v41
	ds_write_b64 v233, v[38:39] offset:32
	v_pk_mul_f32 v[38:39], v[64:65], v[0:1]
	v_pk_mul_f32 v[40:41], v[66:67], v[0:1]
	v_pk_mul_f32 v[38:39], v[84:85], v[38:39]
	v_pk_mul_f32 v[40:41], v[82:83], v[40:41]
	v_cvt_pk_bf16_f32 v38, v38, v39
	v_cvt_pk_bf16_f32 v39, v40, v41
	ds_write_b64 v233, v[38:39] offset:48
	v_pk_mul_f32 v[38:39], v[60:61], v[0:1]
	s_nop 0
	v_pk_mul_f32 v[30:31], v[30:31], v[38:39]
	v_pk_mul_f32 v[38:39], v[62:63], v[0:1]
	v_cvt_pk_bf16_f32 v30, v30, v31
	v_pk_mul_f32 v[28:29], v[28:29], v[38:39]
	s_nop 0
	v_cvt_pk_bf16_f32 v31, v28, v29
	v_pk_mul_f32 v[28:29], v[56:57], v[0:1]
	ds_write_b64 v233, v[30:31] offset:64
	v_pk_mul_f32 v[26:27], v[26:27], v[28:29]
	v_pk_mul_f32 v[28:29], v[58:59], v[0:1]
	v_cvt_pk_bf16_f32 v26, v26, v27
	v_pk_mul_f32 v[24:25], v[24:25], v[28:29]
	s_nop 0
	v_cvt_pk_bf16_f32 v27, v24, v25
	v_pk_mul_f32 v[24:25], v[52:53], v[0:1]
	ds_write_b64 v233, v[26:27] offset:80
	v_pk_mul_f32 v[22:23], v[22:23], v[24:25]
	v_pk_mul_f32 v[24:25], v[54:55], v[0:1]
	v_cvt_pk_bf16_f32 v22, v22, v23
	v_pk_mul_f32 v[20:21], v[20:21], v[24:25]
	s_nop 0
	v_cvt_pk_bf16_f32 v23, v20, v21
	v_pk_mul_f32 v[20:21], v[48:49], v[0:1]
	v_pk_mul_f32 v[0:1], v[50:51], v[0:1]
	v_pk_mul_f32 v[18:19], v[18:19], v[20:21]
	v_pk_mul_f32 v[0:1], v[16:17], v[0:1]
	v_cvt_pk_bf16_f32 v18, v18, v19
	v_cvt_pk_bf16_f32 v19, v0, v1
	v_cvt_pk_bf16_f32 v0, v34, v35
	v_cvt_pk_bf16_f32 v1, v32, v33
	ds_write_b64 v233, v[0:1] offset:128
	v_cvt_pk_bf16_f32 v0, v14, v15
	v_cvt_pk_bf16_f32 v1, v4, v12
	ds_write_b64 v233, v[0:1] offset:144
	v_cvt_pk_bf16_f32 v0, v2, v3
	v_cvt_pk_bf16_f32 v1, v8, v9
	ds_write_b64 v233, v[0:1] offset:160
	v_cvt_pk_bf16_f32 v0, v6, v7
	v_cvt_pk_bf16_f32 v1, v10, v13
	ds_write_b64 v233, v[22:23] offset:96
	ds_write_b64 v233, v[18:19] offset:112
	ds_write_b64 v233, v[0:1] offset:176
	s_waitcnt lgkmcnt(0)
	ds_read_b128 v[200:203], v236 offset:0
	ds_read_b128 v[204:207], v236 offset:1664
	ds_read_b128 v[208:211], v236 offset:3328
	ds_read_b128 v[212:215], v236 offset:4992
	ds_read_b128 v[216:219], v239 offset:0
	ds_read_b128 v[220:223], v239 offset:3328
	s_waitcnt lgkmcnt(5)
	global_store_dwordx4 v[244:245], v[200:203], off
	v_lshl_add_u64 v[244:245], v[244:245], 0, v[196:197]
	s_waitcnt lgkmcnt(4)
	global_store_dwordx4 v[244:245], v[204:207], off
	v_lshl_add_u64 v[244:245], v[244:245], 0, v[196:197]
	s_waitcnt lgkmcnt(3)
	global_store_dwordx4 v[244:245], v[208:211], off
	v_lshl_add_u64 v[244:245], v[244:245], 0, v[196:197]
	s_waitcnt lgkmcnt(2)
	global_store_dwordx4 v[244:245], v[212:215], off
	s_waitcnt lgkmcnt(1)
	global_store_dwordx4 v[198:199], v[216:219], off
	v_lshl_add_u64 v[198:199], v[198:199], 0, v[194:195]
	s_waitcnt lgkmcnt(0)
	global_store_dwordx4 v[198:199], v[220:223], off
